# prep: DFT-fold tile staging loads batched (16 in flight) and the non-MoE conversion tiles spread over blocks 192..511
# speedup vs baseline: 1.0022x; 1.0022x over previous
; __device__ __forceinline__ int tid_() { int t = threadIdx.x; asm volatile("" : "+v"(t)); return t; }
; __device__ __forceinline__ void fold_item(const Params& p, int it, unsigned char* smem) {
;   float* tile = (float*)smem;
;   float* ct = tile + 64 * 65;
;   const int t = tid_();
;   const int l = it >> 6, rem = it & 63, g = rem >> 4, k0 = (rem & 15) * 64;
; #pragma unroll
;   for (int i = 0; i < 16; ++i) {
;     const int kk = i * 4 + (t >> 6), d = t & 63;
;     tile[kk * 65 + d] = __builtin_nontemporal_load(p.w_in + (size_t)(l * 1024 + k0 + kk) * 1216 + 512 + g * 64 + d);
;   }
;   if (t < 64) ct[t] = cospif((float)t / 32.f);
.LBB0_16:
	v_mov_b32_e32 v6, v187
	global_load_dwordx2 v[8:9], v[2:3], off offset:48
	s_ashr_i32 s16, s6, 6
	s_lshl_b32 s0, s6, 6
	s_lshl_b32 s4, s6, 2
	s_and_b32 s17, s0, 0x3c0
	s_lshl_b32 s0, s16, 10
	s_and_b32 s15, s4, 0xc0
	v_ashrrev_i32_e32 v13, 6, v6
	s_or_b32 s4, s0, s17
	v_add_u32_e32 v18, s4, v13
	v_and_b32_e32 v7, 63, v6
	s_lshl_b32 s0, s15, 2
	v_lshlrev_b32_e32 v4, 2, v7
	v_cmp_gt_i32_e32 vcc, 64, v6
	s_waitcnt vmcnt(0) lgkmcnt(0)
	v_mad_i64_i32 v[52:53], s[4:5], v18, s7, v[8:9]
	v_lshl_add_u64 v[52:53], v[52:53], 0, s[0:1]
	v_lshl_add_u64 v[52:53], v[52:53], 0, v[4:5]
	s_mov_b32 s19, 0
	s_mul_i32 s18, s7, 4
	v_lshl_add_u64 v[54:55], v[52:53], 0, s[18:19]
	s_mul_i32 s18, s7, 8
	v_lshl_add_u64 v[56:57], v[52:53], 0, s[18:19]
	s_mul_i32 s18, s7, 12
	v_lshl_add_u64 v[58:59], v[52:53], 0, s[18:19]
	s_mul_i32 s18, s7, 16
	v_lshl_add_u64 v[60:61], v[52:53], 0, s[18:19]
	s_mul_i32 s18, s7, 20
	v_lshl_add_u64 v[62:63], v[52:53], 0, s[18:19]
	s_mul_i32 s18, s7, 24
	v_lshl_add_u64 v[64:65], v[52:53], 0, s[18:19]
	s_mul_i32 s18, s7, 28
	v_lshl_add_u64 v[66:67], v[52:53], 0, s[18:19]
	s_mul_i32 s18, s7, 32
	v_lshl_add_u64 v[68:69], v[52:53], 0, s[18:19]
	s_mul_i32 s18, s7, 36
	v_lshl_add_u64 v[70:71], v[52:53], 0, s[18:19]
	s_mul_i32 s18, s7, 40
	v_lshl_add_u64 v[72:73], v[52:53], 0, s[18:19]
	s_mul_i32 s18, s7, 44
	v_lshl_add_u64 v[74:75], v[52:53], 0, s[18:19]
	s_mul_i32 s18, s7, 48
	v_lshl_add_u64 v[76:77], v[52:53], 0, s[18:19]
	s_mul_i32 s18, s7, 52
	v_lshl_add_u64 v[78:79], v[52:53], 0, s[18:19]
	s_mul_i32 s18, s7, 56
	v_lshl_add_u64 v[80:81], v[52:53], 0, s[18:19]
	s_mul_i32 s18, s7, 60
	v_lshl_add_u64 v[82:83], v[52:53], 0, s[18:19]
	global_load_dword v100, v[52:53], off offset:2048 nt
	global_load_dword v101, v[54:55], off offset:2048 nt
	global_load_dword v102, v[56:57], off offset:2048 nt
	global_load_dword v103, v[58:59], off offset:2048 nt
	global_load_dword v104, v[60:61], off offset:2048 nt
	global_load_dword v105, v[62:63], off offset:2048 nt
	global_load_dword v106, v[64:65], off offset:2048 nt
	global_load_dword v107, v[66:67], off offset:2048 nt
	global_load_dword v108, v[68:69], off offset:2048 nt
	global_load_dword v109, v[70:71], off offset:2048 nt
	global_load_dword v110, v[72:73], off offset:2048 nt
	global_load_dword v111, v[74:75], off offset:2048 nt
	global_load_dword v112, v[76:77], off offset:2048 nt
	global_load_dword v113, v[78:79], off offset:2048 nt
	global_load_dword v114, v[80:81], off offset:2048 nt
	global_load_dword v115, v[82:83], off offset:2048 nt
	v_mad_u64_u32 v[14:15], s[4:5], v13, s12, v[4:5]
	s_waitcnt vmcnt(0) lgkmcnt(0)
	ds_write_b32 v14, v100
	ds_write_b32 v14, v101 offset:1040
	ds_write_b32 v14, v102 offset:2080
	ds_write_b32 v14, v103 offset:3120
	ds_write_b32 v14, v104 offset:4160
	ds_write_b32 v14, v105 offset:5200
	ds_write_b32 v14, v106 offset:6240
	ds_write_b32 v14, v107 offset:7280
	ds_write_b32 v14, v108 offset:8320
	ds_write_b32 v14, v109 offset:9360
	ds_write_b32 v14, v110 offset:10400
	ds_write_b32 v14, v111 offset:11440
	ds_write_b32 v14, v112 offset:12480
	ds_write_b32 v14, v113 offset:13520
	ds_write_b32 v14, v114 offset:14560
	ds_write_b32 v14, v115 offset:15600
	s_and_saveexec_b64 s[4:5], vcc
	s_cbranch_execz .LBB0_18
	v_cvt_f32_i32_e32 v4, v6
	v_lshlrev_b32_e32 v6, 2, v6
	v_mul_f32_e32 v4, 0x3d000000, v4
	v_mul_f32_e64 v8, |v4|, 0.5
	v_fract_f32_e32 v9, v8
	v_add_f32_e32 v9, v9, v9
	v_cmp_neq_f32_e32 vcc, s13, v8
	v_cmp_gt_f32_e64 s[18:19], |v4|, 1.0
	s_nop 0
	v_cndmask_b32_e32 v8, 0, v9, vcc
	v_cndmask_b32_e64 v8, |v4|, v8, s[18:19]
	v_add_f32_e32 v9, v8, v8
	v_rndne_f32_e32 v9, v9
	v_fmac_f32_e32 v8, -0.5, v9
	v_mul_f32_e32 v14, v8, v8
	v_fmamk_f32 v15, v14, 0x3e75aa41, v1
	v_fmaak_f32 v15, v14, v15, 0x40234736
	v_fmaak_f32 v15, v14, v15, 0xc0a55e0e
	v_mul_f32_e32 v17, v8, v14
	v_cvt_i32_f32_e32 v9, v9
	v_mul_f32_e32 v15, v17, v15
	v_fmac_f32_e32 v15, 0x40490fdb, v8
	v_fmamk_f32 v8, v14, 0x3d4be544, v10
	v_fmaak_f32 v8, v14, v8, 0xbfaad1da
	v_fmaak_f32 v8, v14, v8, 0x4081e0d3
	v_and_b32_e32 v16, 2, v9
	v_fmaak_f32 v8, v14, v8, 0xc09de9e6
	v_and_b32_e32 v9, 1, v9
	v_fma_f32 v8, v14, v8, 1.0
	v_cmp_eq_u32_e32 vcc, 0, v9
	s_nop 1
	v_cndmask_b32_e64 v8, -v15, v8, vcc
	v_cmp_eq_u32_e32 vcc, 0, v16
	s_nop 1
	v_cndmask_b32_e64 v8, -v8, v8, vcc
	v_cmp_class_f32_e64 vcc, v4, s14
	s_nop 1
	v_cndmask_b32_e32 v4, v12, v8, vcc
	ds_write_b32 v6, v4 offset:16640

; __device__ __forceinline__ int bid_() { int b = blockIdx.x; asm volatile("" : "+s"(b)); return b; }
; __device__ __forceinline__ void conv_item(const Params& p, int it, unsigned char* smem) {
;   const int l = it / 6720;
;   int r = it % 6720;
;   if (r < 240) {
;     const int ct = r >> 4, kt = r & 15;
;     const int c0 = (ct < 8 ? ct : ct + 4) * 64;
;     const int n0 = c0 + (c0 >= 768 ? 256 : 0);
;     convT_tile(p.w_in + (size_t)l * 1024 * 1216, 1216, kt * 64, c0, p.WinT + (size_t)l * 1536 * 1024, 1024, n0, 0, 0, smem);
;     return;
;   }
;   r -= 240;
;   if (r < 48) {
;     const int ct = r >> 2, kt = r & 3;
;     convT_tile(p.w_uq + (size_t)l * 256 * 768, 768, kt * 64, ct * 64, p.WuqT + (size_t)l * 768 * 256, 256, ct * 64, 0, 0, smem, p.q_lora_norm + l * 256);
;     return;
;   }
;   r -= 48;
;   if (r < 32) {
;     const int ct = r >> 1, kt = r & 1;
;     convT_tile(p.w_ukv + (size_t)l * 128 * 1024, 1024, kt * 64, ct * 64, p.WukvT + (size_t)l * 1024 * 128, 128, ct * 64, 0, 0, smem, p.kv_lora_norm + l * 128);
;     return;
;   }
;   r -= 32;
;   if (r < 256) {
;     const int ct = r >> 4, kt = r & 15;
;     convT_tile(p.w_out + (size_t)l * 1024 * 1024, 1024, kt * 64, ct * 64, p.WoutT + (size_t)l * 1024 * 1024, 1024, ct * 64, 0, 0, smem);
;     return;
;   }
;   r -= 256;
;   if (r < 4096) {
; __device__ __forceinline__ void phase_prep(const Params& p, unsigned char* smem) {
;   const int G = gridDim.x;
;   int t = bid_();
;   for (; t < 192; t += G) ada_item(p, t, smem);
;   t -= 192;
;   for (; t < 128; t += G) fold_item(p, t, smem);
;   t -= 128;
;   for (; t < 13440; t += G) conv_item(p, t, smem);
;   t -= 13440;
;   for (; t < 2336; t += G) elem_item(p, t);
; }
.LBB0_23:
	s_add_i32 s14, s2, 64
	s_and_b32 s14, s14, 0x1ff
	s_addk_i32 s14, 0x3480
	s_cmp_lt_u32 s2, 0xc0
	s_cbranch_scc1 .LBB0_62
	s_sub_i32 s14, s2, 0x140
	s_cmp_lt_u32 s2, 0x140
	s_cselect_b32 s14, s2, s14
	s_load_dwordx2 s[0:1], s[64:65], 0x1b0
	s_lshl_b32 s15, s14, 6
	s_lshl_b32 s17, s14, 4
	s_lshl_b32 s19, s14, 5
	s_lshl_b32 s21, s14, 2
	s_waitcnt lgkmcnt(0)
	s_mov_b64 s[4:5], s[0:1]
	s_movk_i32 s4, 0x140
	s_lshl_b32 s0, s14, 3
	s_lshl_b32 s16, s4, 6
	s_lshl_b32 s18, s4, 4
	s_lshl_b32 s20, s4, 5
	s_lshl_b32 s22, s4, 2
	s_add_i32 s23, s0, 0xffff6e00
	s_lshl_b32 s24, s4, 3
	s_mov_b32 s5, 0
	v_mov_b32_e32 v19, 0
	s_mov_b32 s25, 0x10000
	s_mov_b32 s26, 0x20000
	s_mov_b32 s27, 0x30000
	s_movk_i32 s28, 0x104
	s_movk_i32 s29, 0x90
	s_mov_b32 s30, 0x8000
	s_mov_b32 s31, 0x18000
	s_movk_i32 s33, 0xc00
	s_movk_i32 s34, 0x1300
	v_mov_b32_e32 v1, 0xc0000
	v_mov_b32_e32 v25, 0x60000
	v_mov_b32_e32 v27, 0x4c0000
	v_mov_b32_e32 v28, 0x300000
	s_branch .LBB0_26
.LBB0_25:
	s_load_dwordx2 s[0:1], s[64:65], 0x1b0
	s_add_i32 s15, s15, s16
	s_add_i32 s17, s17, s18
	s_add_i32 s19, s19, s20
	s_add_i32 s21, s21, s22
	s_waitcnt lgkmcnt(0)
	s_addk_i32 s14, 0x140
	s_add_i32 s23, s23, s24
	s_cmpk_lt_i32 s14, 0x3480
	s_cbranch_scc0 .LBB0_62
.LBB0_26:
	s_mul_hi_i32 s0, s14, 0x9c09c09d
	s_add_i32 s0, s0, s14
	s_lshr_b32 s1, s0, 31
	s_ashr_i32 s0, s0, 12
	s_add_i32 s6, s0, s1
	s_mul_i32 s0, s6, 0xffffe5c0
	s_add_i32 s35, s14, s0
	s_cmpk_gt_i32 s35, 0xef
	s_mov_b64 s[0:1], -1
	s_cbranch_scc0 .LBB0_60
	s_cmpk_gt_u32 s35, 0x11f
	s_cbranch_scc0 .LBB0_49
	s_cmpk_gt_u32 s35, 0x13f
	s_cbranch_scc0 .LBB0_38
	s_cmpk_gt_u32 s35, 0x23f
	s_cbranch_scc0 .LBB0_35
	s_cmpk_gt_i32 s14, 0x1a3f
	s_cbranch_scc1 .Lprep_convdone
	s_sub_i32 s14, s2, 0x140
	s_cmp_lt_u32 s2, 0x140
	s_cselect_b32 s14, s2, s14
	s_addk_i32 s14, 0x1a40
	s_lshl_b32 s15, s14, 6
	s_lshl_b32 s17, s14, 4
	s_lshl_b32 s19, s14, 5
	s_lshl_b32 s21, s14, 2
	s_lshl_b32 s0, s14, 3
	s_add_i32 s23, s0, 0xffff6e00
	s_branch .LBB0_26
